# compress prompt piece: all 32 operand loads issued before the MFMA chain
# baseline (speedup 1.0000x reference)
; #define LAS __attribute__((address_space(3)))
; __device__ __forceinline__ unsigned f2bf(float f) { return pk2(f, 0.f) & 0xffffu; }
; __device__ __forceinline__ int keypos(int key) { return (key & ~12) | ((key & 4) << 1) | ((key & 8) >> 1); }
; __device__ __forceinline__ void compress_prompt_piece(Frame& F, int l, int piece) {
;     const int lane = F.lane, w = F.wave, col = lane & 15, q = lane >> 4, nl = col >> 2, k = col & 3;
;     const int ntile = piece >> 3, j = (piece >> 2) & 1, et = piece & 3, b = ntile >> 4, n0 = (ntile & 15) * 4;
;     const bf16_t* wphi = (const bf16_t*)(F.ws + WS_WPHI + l * al1m(SZ_WPHI)) + ((size_t)(j * 64) * 64 + 16 * et + col) * 64 + 8 * q;
;     const bf16_t* xp = (const bf16_t*)(F.ws + WS_P) + (size_t)(b * SEQ + (n0 + nl) * 64) * NPROJ + C_CK + j * 256 + k * 64 + 8 * q;
;     bf16x8 a[16], x[16];
; #pragma unroll
;     for (int li = 0; li < 8; ++li)
; #pragma unroll
;         for (int dc = 0; dc < 2; ++dc) { const int lpos = w * 8 + li;
;             a[li * 2 + dc] = *(const bf16x8*)(wphi + (size_t)lpos * 4096 + 32 * dc); x[li * 2 + dc] = *(const bf16x8*)(xp + (size_t)lpos * NPROJ + 32 * dc); }
;     f32x4 acc = {0.f, 0.f, 0.f, 0.f};
; #pragma unroll
;     for (int i = 0; i < 16; ++i) acc = __builtin_amdgcn_mfma_f32_16x16x32_bf16(a[i], x[i], acc, 0, 0, 0);
;     LAS float* red = (LAS float*)F.lds;
;     __syncthreads();
; #pragma unroll
;     for (int i = 0; i < 4; ++i) red[(w * 4 + i) * 64 + lane] = acc[i];
;     __syncthreads();
;     if (F.tid < 256) { const int i = F.tid >> 6, ln = F.tid & 63; float s = 0.f;
; #pragma unroll
;         for (int ww = 0; ww < 8; ++ww) s += red[(ww * 4 + i) * 64 + ln];
;         const int e = 16 * et + 4 * (ln >> 4) + i, cc = ln & 15, blk = n0 + (cc >> 2), kk = cc & 3;
;         s += ((const LAS float*)(F.lds + 131072))[j * 64 + e];
;         if (j == 0) ((bf16_t*)(F.ws + WS_KCP))[(size_t)(b * 4 + kk) * 4096 + (e >> 3) * 512 + blk * 8 + (e & 7)] = (bf16_t)f2bf(s);
;         else { const int pos = keypos(blk); ((bf16_t*)(F.ws + WS_VCTP))[(size_t)(b * 4 + kk) * 4096 + (pos >> 3) * 512 + e * 8 + (pos & 7)] = (bf16_t)f2bf(s); } }
.LBB0_589:
	s_bfe_u32 s34, s15, 0x10002
	s_lshr_b32 s17, s15, 1
	s_lshl_b32 s4, s34, 12
	s_and_b32 s35, s14, 48
	s_ashr_i32 s16, s15, 7
	s_and_b32 s36, s17, 60
	s_or_b32 s4, s4, s35
	v_or_b32_e32 v7, s4, v230
	s_lshl_b32 s4, s16, 12
	v_or_b32_e32 v22, s36, v231
	v_lshlrev_b32_e32 v98, 7, v7
	v_lshl_or_b32 v7, v22, 6, s4
	v_mov_b64_e32 v[8:9], s[54:55]
	v_mad_i64_i32 v[8:9], s[30:31], v7, s87, v[8:9]
	s_lshl_b32 s4, s34, 9
	v_lshl_add_u64 v[60:61], v[4:5], 0, v[98:99]
	v_lshl_add_u64 v[8:9], v[8:9], 0, s[4:5]
	v_mov_b32_e32 v7, v99
	v_lshl_add_u64 v[8:9], v[8:9], 0, v[6:7]
	v_lshl_add_u64 v[12:13], v[8:9], 0, v[2:3]
	s_mov_b64 s[30:31], 0xc801800
	v_lshl_add_u64 v[62:63], v[12:13], 0, s[30:31]
	v_lshl_add_u64 v[100:101], v[60:61], 0, s[56:57]
	global_load_dwordx4 v[132:135], v[100:101], off
	global_load_dwordx4 v[136:139], v[100:101], off offset:64
	v_lshl_add_u64 v[102:103], v[62:63], 0, s[22:23]
	global_load_dwordx4 v[8:11], v[102:103], off
	global_load_dwordx4 v[12:15], v[102:103], off offset:64
	v_lshl_add_u64 v[100:101], v[60:61], 0, s[44:45]
	global_load_dwordx4 v[140:143], v[100:101], off
	global_load_dwordx4 v[144:147], v[100:101], off offset:64
	v_lshl_add_u64 v[102:103], v[62:63], 0, s[46:47]
	global_load_dwordx4 v[16:19], v[102:103], off
	global_load_dwordx4 v[24:27], v[102:103], off offset:64
	v_lshl_add_u64 v[100:101], v[60:61], 0, s[60:61]
	global_load_dwordx4 v[148:151], v[100:101], off
	global_load_dwordx4 v[152:155], v[100:101], off offset:64
	v_lshl_add_u64 v[102:103], v[62:63], 0, s[64:65]
	global_load_dwordx4 v[28:31], v[102:103], off
	global_load_dwordx4 v[32:35], v[102:103], off offset:64
	v_lshl_add_u64 v[100:101], v[60:61], 0, s[66:67]
	global_load_dwordx4 v[156:159], v[100:101], off
	global_load_dwordx4 v[160:163], v[100:101], off offset:64
	v_lshl_add_u64 v[102:103], v[62:63], 0, s[68:69]
	global_load_dwordx4 v[36:39], v[102:103], off
	global_load_dwordx4 v[40:43], v[102:103], off offset:64
	v_lshl_add_u64 v[100:101], v[60:61], 0, s[70:71]
	global_load_dwordx4 v[164:167], v[100:101], off
	global_load_dwordx4 v[168:171], v[100:101], off offset:64
	v_lshl_add_u64 v[102:103], v[62:63], 0, s[72:73]
	global_load_dwordx4 v[44:47], v[102:103], off
	global_load_dwordx4 v[48:51], v[102:103], off offset:64
	v_lshl_add_u64 v[100:101], v[60:61], 0, s[74:75]
	global_load_dwordx4 v[172:175], v[100:101], off
	global_load_dwordx4 v[176:179], v[100:101], off offset:64
	v_lshl_add_u64 v[102:103], v[62:63], 0, s[76:77]
	global_load_dwordx4 v[52:55], v[102:103], off
	global_load_dwordx4 v[56:59], v[102:103], off offset:64
	v_lshl_add_u64 v[100:101], v[60:61], 0, s[24:25]
	global_load_dwordx4 v[180:183], v[100:101], off
	global_load_dwordx4 v[184:187], v[100:101], off offset:64
	v_lshl_add_u64 v[102:103], v[62:63], 0, s[26:27]
	global_load_dwordx4 v[64:67], v[102:103], off
	global_load_dwordx4 v[68:71], v[102:103], off offset:64
	v_lshl_add_u64 v[100:101], v[60:61], 0, s[58:59]
	global_load_dwordx4 v[188:191], v[100:101], off
	global_load_dwordx4 v[192:195], v[100:101], off offset:64
	v_lshl_add_u64 v[102:103], v[62:63], 0, s[28:29]
	global_load_dwordx4 v[72:75], v[102:103], off
	global_load_dwordx4 v[76:79], v[102:103], off offset:64
	v_add_u32_e32 v7, s8, v207
	s_waitcnt vmcnt(29)
	v_mfma_f32_16x16x32_bf16 v[104:107], v[132:135], v[8:11], 0
	s_waitcnt vmcnt(28)
	v_mfma_f32_16x16x32_bf16 v[104:107], v[136:139], v[12:15], v[104:107]
	s_waitcnt vmcnt(25)
	v_mfma_f32_16x16x32_bf16 v[104:107], v[140:143], v[16:19], v[104:107]
	s_waitcnt vmcnt(24)
	v_mfma_f32_16x16x32_bf16 v[104:107], v[144:147], v[24:27], v[104:107]
	s_waitcnt vmcnt(21)
	v_mfma_f32_16x16x32_bf16 v[104:107], v[148:151], v[28:31], v[104:107]
	s_waitcnt vmcnt(20)
	v_mfma_f32_16x16x32_bf16 v[104:107], v[152:155], v[32:35], v[104:107]
	s_waitcnt vmcnt(17)
	v_mfma_f32_16x16x32_bf16 v[104:107], v[156:159], v[36:39], v[104:107]
	s_waitcnt vmcnt(16)
	v_mfma_f32_16x16x32_bf16 v[104:107], v[160:163], v[40:43], v[104:107]
	s_waitcnt vmcnt(13)
	v_mfma_f32_16x16x32_bf16 v[104:107], v[164:167], v[44:47], v[104:107]
	s_waitcnt vmcnt(12)
	v_mfma_f32_16x16x32_bf16 v[104:107], v[168:171], v[48:51], v[104:107]
	s_waitcnt vmcnt(9)
	v_mfma_f32_16x16x32_bf16 v[104:107], v[172:175], v[52:55], v[104:107]
	s_waitcnt vmcnt(8)
	v_mfma_f32_16x16x32_bf16 v[104:107], v[176:179], v[56:59], v[104:107]
	s_waitcnt vmcnt(5)
	v_mfma_f32_16x16x32_bf16 v[104:107], v[180:183], v[64:67], v[104:107]
	s_waitcnt vmcnt(4)
	v_mfma_f32_16x16x32_bf16 v[104:107], v[184:187], v[68:71], v[104:107]
	s_waitcnt vmcnt(1)
	v_mfma_f32_16x16x32_bf16 v[104:107], v[188:191], v[72:75], v[104:107]
	s_waitcnt vmcnt(0)
	v_mfma_f32_16x16x32_bf16 v[104:107], v[192:195], v[76:79], v[104:107]
	s_barrier
	s_nop 7
	v_mov_b32_e32 v8, v104
	v_mov_b32_e32 v9, v105
	v_mov_b32_e32 v10, v106
	v_mov_b32_e32 v11, v107
	ds_write2st64_b32 v7, v8, v9 offset1:1
	ds_write2st64_b32 v7, v10, v11 offset0:2 offset1:3
	s_waitcnt lgkmcnt(0)
	s_barrier
	s_and_saveexec_b64 s[30:31], s[40:41]
	s_cbranch_execz .LBB0_588
	s_lshl_b32 s4, s34, 8
	v_or_b32_e32 v7, s35, v1
	v_add_u32_e32 v23, v7, v21
	s_add_i32 s4, s4, 0
	ds_read2st64_b32 v[14:15], v20 offset1:4
	ds_read2st64_b32 v[12:13], v20 offset0:8 offset1:12
	ds_read2st64_b32 v[10:11], v20 offset0:16 offset1:20
	ds_read2st64_b32 v[8:9], v20 offset0:24 offset1:28
	v_lshl_add_u32 v7, v23, 2, s4
	v_add_u32_e32 v7, 0x20000, v7
	ds_read_b32 v7, v7
	s_cmp_lg_u32 s34, 0
	s_mov_b64 s[34:35], -1
	s_cbranch_scc0 .LBB0_592
	s_and_b32 s4, s17, 48
	s_lshl_b32 s17, s36, 1
	s_and_b32 s17, s17, 8
	s_or_b32 s4, s17, s4
	s_lshr_b32 s34, s15, 2
	s_lshl_b32 s4, s4, 6
	v_lshlrev_b32_e32 v16, 3, v23
	v_ashrrev_i32_e32 v17, 31, v16
	v_and_or_b32 v98, s34, 4, v231
	s_mov_b64 s[34:35], 0
	v_mov_b64_e32 v[18:19], s[4:5]
